# write-through (sc0 sc1) stores for the final output tile in the fused epilogue
# baseline (speedup 1.0000x reference)
.Lf11_w1_a:
	global_load_dwordx4 v[226:229], v131, s[8:9] sc1
	global_load_dwordx4 v[230:233], v131, s[8:9] offset:1024 sc1
	global_load_dwordx4 v[234:237], v131, s[8:9] offset:2048 sc1
	global_load_dwordx4 v[238:241], v131, s[8:9] offset:3072 sc1
	global_load_dwordx4 v[172:175], v131, s[74:75] sc1
	global_load_dwordx4 v[176:179], v131, s[74:75] offset:1024 sc1
	global_load_dwordx4 v[180:183], v131, s[74:75] offset:2048 sc1
	global_load_dwordx4 v[184:187], v131, s[74:75] offset:3072 sc1
	s_mov_b64 s[76:77], s[24:25]
	s_mov_b32 s84, 0x3a800000
	v_mov_b32_e32 v133, 0x358637bd
	s_waitcnt vmcnt(7)
	v_add_f32_e32 v226, v226, v227
	v_add_f32_e32 v228, v228, v229
	v_add_f32_e32 v156, v226, v228
	s_waitcnt vmcnt(6)
	v_add_f32_e32 v230, v230, v231
	v_add_f32_e32 v232, v232, v233
	v_add_f32_e32 v157, v230, v232
	s_waitcnt vmcnt(5)
	v_add_f32_e32 v234, v234, v235
	v_add_f32_e32 v236, v236, v237
	v_add_f32_e32 v158, v234, v236
	s_waitcnt vmcnt(4)
	v_add_f32_e32 v238, v238, v239
	v_add_f32_e32 v240, v240, v241
	v_add_f32_e32 v159, v238, v240
	s_waitcnt vmcnt(3)
	v_add_f32_e32 v172, v172, v173
	v_add_f32_e32 v174, v174, v175
	v_add_f32_e32 v160, v172, v174
	s_waitcnt vmcnt(2)
	v_add_f32_e32 v176, v176, v177
	v_add_f32_e32 v178, v178, v179
	v_add_f32_e32 v161, v176, v178
	s_waitcnt vmcnt(1)
	v_add_f32_e32 v180, v180, v181
	v_add_f32_e32 v182, v182, v183
	v_add_f32_e32 v162, v180, v182
	s_waitcnt vmcnt(0)
	v_add_f32_e32 v184, v184, v185
	v_add_f32_e32 v186, v186, v187
	v_add_f32_e32 v163, v184, v186
	ds_bpermute_b32 v136, v134, v156
	ds_bpermute_b32 v137, v134, v157
	ds_bpermute_b32 v138, v134, v158
	ds_bpermute_b32 v139, v134, v159
	ds_bpermute_b32 v188, v134, v160
	ds_bpermute_b32 v189, v134, v161
	ds_bpermute_b32 v190, v134, v162
	ds_bpermute_b32 v191, v134, v163
	s_waitcnt lgkmcnt(0)
	v_add_f32_e32 v156, v156, v136
	v_add_f32_e32 v157, v157, v137
	v_add_f32_e32 v158, v158, v138
	v_add_f32_e32 v159, v159, v139
	v_add_f32_e32 v160, v160, v188
	v_add_f32_e32 v161, v161, v189
	v_add_f32_e32 v162, v162, v190
	v_add_f32_e32 v163, v163, v191
	ds_bpermute_b32 v136, v135, v156
	ds_bpermute_b32 v137, v135, v157
	ds_bpermute_b32 v138, v135, v158
	ds_bpermute_b32 v139, v135, v159
	ds_bpermute_b32 v188, v135, v160
	ds_bpermute_b32 v189, v135, v161
	ds_bpermute_b32 v190, v135, v162
	ds_bpermute_b32 v191, v135, v163
	s_waitcnt lgkmcnt(0)
	v_add_f32_e32 v156, v156, v136
	v_add_f32_e32 v157, v157, v137
	v_add_f32_e32 v158, v158, v138
	v_add_f32_e32 v159, v159, v139
	v_add_f32_e32 v160, v160, v188
	v_add_f32_e32 v161, v161, v189
	v_add_f32_e32 v162, v162, v190
	v_add_f32_e32 v163, v163, v191
	v_fma_f32 v156, v156, s84, v133
	v_fma_f32 v157, v157, s84, v133
	v_fma_f32 v158, v158, s84, v133
	v_fma_f32 v159, v159, s84, v133
	v_fma_f32 v160, v160, s84, v133
	v_fma_f32 v161, v161, s84, v133
	v_fma_f32 v162, v162, s84, v133
	v_fma_f32 v163, v163, s84, v133
	v_rsq_f32_e32 v194, v156
	v_rsq_f32_e32 v196, v157
	v_rsq_f32_e32 v198, v158
	v_rsq_f32_e32 v200, v159
	v_rsq_f32_e32 v202, v160
	v_rsq_f32_e32 v204, v161
	v_rsq_f32_e32 v206, v162
	v_rsq_f32_e32 v208, v163
	s_nop 0
	v_pk_mul_f32 v[124:125], v[124:125], v[194:195] op_sel_hi:[1,0]
	v_pk_mul_f32 v[126:127], v[126:127], v[194:195] op_sel_hi:[1,0]
	v_pk_mul_f32 v[120:121], v[120:121], v[194:195] op_sel_hi:[1,0]
	v_pk_mul_f32 v[122:123], v[122:123], v[194:195] op_sel_hi:[1,0]
	v_pk_mul_f32 v[116:117], v[116:117], v[194:195] op_sel_hi:[1,0]
	v_pk_mul_f32 v[118:119], v[118:119], v[194:195] op_sel_hi:[1,0]
	v_pk_mul_f32 v[112:113], v[112:113], v[194:195] op_sel_hi:[1,0]
	v_pk_mul_f32 v[114:115], v[114:115], v[194:195] op_sel_hi:[1,0]
	v_pk_mul_f32 v[124:125], v[124:125], v[210:211]
	v_pk_mul_f32 v[126:127], v[126:127], v[212:213]
	v_pk_mul_f32 v[120:121], v[120:121], v[214:215]
	v_pk_mul_f32 v[122:123], v[122:123], v[216:217]
	v_pk_mul_f32 v[116:117], v[116:117], v[218:219]
	v_pk_mul_f32 v[118:119], v[118:119], v[220:221]
	v_pk_mul_f32 v[112:113], v[112:113], v[222:223]
	v_pk_mul_f32 v[114:115], v[114:115], v[224:225]
	global_store_dwordx4 v129, v[124:127], s[76:77] sc0 sc1
	global_store_dwordx4 v129, v[120:123], s[76:77] offset:16 sc0 sc1
	global_store_dwordx4 v129, v[116:119], s[76:77] offset:128 sc0 sc1
	global_store_dwordx4 v129, v[112:115], s[76:77] offset:144 sc0 sc1
	s_add_u32 s76, s76, 0x10000
	s_addc_u32 s77, s77, 0
	v_pk_mul_f32 v[108:109], v[108:109], v[196:197] op_sel_hi:[1,0]
	v_pk_mul_f32 v[110:111], v[110:111], v[196:197] op_sel_hi:[1,0]
	v_pk_mul_f32 v[104:105], v[104:105], v[196:197] op_sel_hi:[1,0]
	v_pk_mul_f32 v[106:107], v[106:107], v[196:197] op_sel_hi:[1,0]
	v_pk_mul_f32 v[100:101], v[100:101], v[196:197] op_sel_hi:[1,0]
	v_pk_mul_f32 v[102:103], v[102:103], v[196:197] op_sel_hi:[1,0]
	v_pk_mul_f32 v[96:97], v[96:97], v[196:197] op_sel_hi:[1,0]
	v_pk_mul_f32 v[98:99], v[98:99], v[196:197] op_sel_hi:[1,0]
	v_pk_mul_f32 v[108:109], v[108:109], v[210:211]
	v_pk_mul_f32 v[110:111], v[110:111], v[212:213]
	v_pk_mul_f32 v[104:105], v[104:105], v[214:215]
	v_pk_mul_f32 v[106:107], v[106:107], v[216:217]
	v_pk_mul_f32 v[100:101], v[100:101], v[218:219]
	v_pk_mul_f32 v[102:103], v[102:103], v[220:221]
	v_pk_mul_f32 v[96:97], v[96:97], v[222:223]
	v_pk_mul_f32 v[98:99], v[98:99], v[224:225]
	global_store_dwordx4 v129, v[108:111], s[76:77] sc0 sc1
	global_store_dwordx4 v129, v[104:107], s[76:77] offset:16 sc0 sc1
	global_store_dwordx4 v129, v[100:103], s[76:77] offset:128 sc0 sc1
	global_store_dwordx4 v129, v[96:99], s[76:77] offset:144 sc0 sc1
	s_add_u32 s76, s76, 0x10000
	s_addc_u32 s77, s77, 0
	v_pk_mul_f32 v[92:93], v[92:93], v[198:199] op_sel_hi:[1,0]
	v_pk_mul_f32 v[94:95], v[94:95], v[198:199] op_sel_hi:[1,0]
	v_pk_mul_f32 v[88:89], v[88:89], v[198:199] op_sel_hi:[1,0]
	v_pk_mul_f32 v[90:91], v[90:91], v[198:199] op_sel_hi:[1,0]
	v_pk_mul_f32 v[84:85], v[84:85], v[198:199] op_sel_hi:[1,0]
	v_pk_mul_f32 v[86:87], v[86:87], v[198:199] op_sel_hi:[1,0]
	v_pk_mul_f32 v[80:81], v[80:81], v[198:199] op_sel_hi:[1,0]
	v_pk_mul_f32 v[82:83], v[82:83], v[198:199] op_sel_hi:[1,0]
	v_pk_mul_f32 v[92:93], v[92:93], v[210:211]
	v_pk_mul_f32 v[94:95], v[94:95], v[212:213]
	v_pk_mul_f32 v[88:89], v[88:89], v[214:215]
	v_pk_mul_f32 v[90:91], v[90:91], v[216:217]
	v_pk_mul_f32 v[84:85], v[84:85], v[218:219]
	v_pk_mul_f32 v[86:87], v[86:87], v[220:221]
	v_pk_mul_f32 v[80:81], v[80:81], v[222:223]
	v_pk_mul_f32 v[82:83], v[82:83], v[224:225]
	global_store_dwordx4 v129, v[92:95], s[76:77] sc0 sc1
	global_store_dwordx4 v129, v[88:91], s[76:77] offset:16 sc0 sc1
	global_store_dwordx4 v129, v[84:87], s[76:77] offset:128 sc0 sc1
	global_store_dwordx4 v129, v[80:83], s[76:77] offset:144 sc0 sc1
	s_add_u32 s76, s76, 0x10000
	s_addc_u32 s77, s77, 0
	v_pk_mul_f32 v[76:77], v[76:77], v[200:201] op_sel_hi:[1,0]
	v_pk_mul_f32 v[78:79], v[78:79], v[200:201] op_sel_hi:[1,0]
	v_pk_mul_f32 v[72:73], v[72:73], v[200:201] op_sel_hi:[1,0]
	v_pk_mul_f32 v[74:75], v[74:75], v[200:201] op_sel_hi:[1,0]
	v_pk_mul_f32 v[68:69], v[68:69], v[200:201] op_sel_hi:[1,0]
	v_pk_mul_f32 v[70:71], v[70:71], v[200:201] op_sel_hi:[1,0]
	v_pk_mul_f32 v[64:65], v[64:65], v[200:201] op_sel_hi:[1,0]
	v_pk_mul_f32 v[66:67], v[66:67], v[200:201] op_sel_hi:[1,0]
	v_pk_mul_f32 v[76:77], v[76:77], v[210:211]
	v_pk_mul_f32 v[78:79], v[78:79], v[212:213]
	v_pk_mul_f32 v[72:73], v[72:73], v[214:215]
	v_pk_mul_f32 v[74:75], v[74:75], v[216:217]
	v_pk_mul_f32 v[68:69], v[68:69], v[218:219]
	v_pk_mul_f32 v[70:71], v[70:71], v[220:221]
	v_pk_mul_f32 v[64:65], v[64:65], v[222:223]
	v_pk_mul_f32 v[66:67], v[66:67], v[224:225]
	global_store_dwordx4 v129, v[76:79], s[76:77] sc0 sc1
	global_store_dwordx4 v129, v[72:75], s[76:77] offset:16 sc0 sc1
	global_store_dwordx4 v129, v[68:71], s[76:77] offset:128 sc0 sc1
	global_store_dwordx4 v129, v[64:67], s[76:77] offset:144 sc0 sc1
	s_add_u32 s76, s76, 0x50000
	s_addc_u32 s77, s77, 0
	v_pk_mul_f32 v[60:61], v[60:61], v[202:203] op_sel_hi:[1,0]
	v_pk_mul_f32 v[62:63], v[62:63], v[202:203] op_sel_hi:[1,0]
	v_pk_mul_f32 v[56:57], v[56:57], v[202:203] op_sel_hi:[1,0]
	v_pk_mul_f32 v[58:59], v[58:59], v[202:203] op_sel_hi:[1,0]
	v_pk_mul_f32 v[52:53], v[52:53], v[202:203] op_sel_hi:[1,0]
	v_pk_mul_f32 v[54:55], v[54:55], v[202:203] op_sel_hi:[1,0]
	v_pk_mul_f32 v[48:49], v[48:49], v[202:203] op_sel_hi:[1,0]
	v_pk_mul_f32 v[50:51], v[50:51], v[202:203] op_sel_hi:[1,0]
	v_pk_mul_f32 v[60:61], v[60:61], v[210:211]
	v_pk_mul_f32 v[62:63], v[62:63], v[212:213]
	v_pk_mul_f32 v[56:57], v[56:57], v[214:215]
	v_pk_mul_f32 v[58:59], v[58:59], v[216:217]
	v_pk_mul_f32 v[52:53], v[52:53], v[218:219]
	v_pk_mul_f32 v[54:55], v[54:55], v[220:221]
	v_pk_mul_f32 v[48:49], v[48:49], v[222:223]
	v_pk_mul_f32 v[50:51], v[50:51], v[224:225]
	global_store_dwordx4 v129, v[60:63], s[76:77] sc0 sc1
	global_store_dwordx4 v129, v[56:59], s[76:77] offset:16 sc0 sc1
	global_store_dwordx4 v129, v[52:55], s[76:77] offset:128 sc0 sc1
	global_store_dwordx4 v129, v[48:51], s[76:77] offset:144 sc0 sc1
	s_add_u32 s76, s76, 0x10000
	s_addc_u32 s77, s77, 0
	v_pk_mul_f32 v[44:45], v[44:45], v[204:205] op_sel_hi:[1,0]
	v_pk_mul_f32 v[46:47], v[46:47], v[204:205] op_sel_hi:[1,0]
	v_pk_mul_f32 v[40:41], v[40:41], v[204:205] op_sel_hi:[1,0]
	v_pk_mul_f32 v[42:43], v[42:43], v[204:205] op_sel_hi:[1,0]
	v_pk_mul_f32 v[36:37], v[36:37], v[204:205] op_sel_hi:[1,0]
	v_pk_mul_f32 v[38:39], v[38:39], v[204:205] op_sel_hi:[1,0]
	v_pk_mul_f32 v[32:33], v[32:33], v[204:205] op_sel_hi:[1,0]
	v_pk_mul_f32 v[34:35], v[34:35], v[204:205] op_sel_hi:[1,0]
	v_pk_mul_f32 v[44:45], v[44:45], v[210:211]
	v_pk_mul_f32 v[46:47], v[46:47], v[212:213]
	v_pk_mul_f32 v[40:41], v[40:41], v[214:215]
	v_pk_mul_f32 v[42:43], v[42:43], v[216:217]
	v_pk_mul_f32 v[36:37], v[36:37], v[218:219]
	v_pk_mul_f32 v[38:39], v[38:39], v[220:221]
	v_pk_mul_f32 v[32:33], v[32:33], v[222:223]
	v_pk_mul_f32 v[34:35], v[34:35], v[224:225]
	global_store_dwordx4 v129, v[44:47], s[76:77] sc0 sc1
	global_store_dwordx4 v129, v[40:43], s[76:77] offset:16 sc0 sc1
	global_store_dwordx4 v129, v[36:39], s[76:77] offset:128 sc0 sc1
	global_store_dwordx4 v129, v[32:35], s[76:77] offset:144 sc0 sc1
	s_add_u32 s76, s76, 0x10000
	s_addc_u32 s77, s77, 0
	v_pk_mul_f32 v[28:29], v[28:29], v[206:207] op_sel_hi:[1,0]
	v_pk_mul_f32 v[30:31], v[30:31], v[206:207] op_sel_hi:[1,0]
	v_pk_mul_f32 v[24:25], v[24:25], v[206:207] op_sel_hi:[1,0]
	v_pk_mul_f32 v[26:27], v[26:27], v[206:207] op_sel_hi:[1,0]
	v_pk_mul_f32 v[20:21], v[20:21], v[206:207] op_sel_hi:[1,0]
	v_pk_mul_f32 v[22:23], v[22:23], v[206:207] op_sel_hi:[1,0]
	v_pk_mul_f32 v[16:17], v[16:17], v[206:207] op_sel_hi:[1,0]
	v_pk_mul_f32 v[18:19], v[18:19], v[206:207] op_sel_hi:[1,0]
	v_pk_mul_f32 v[28:29], v[28:29], v[210:211]
	v_pk_mul_f32 v[30:31], v[30:31], v[212:213]
	v_pk_mul_f32 v[24:25], v[24:25], v[214:215]
	v_pk_mul_f32 v[26:27], v[26:27], v[216:217]
	v_pk_mul_f32 v[20:21], v[20:21], v[218:219]
	v_pk_mul_f32 v[22:23], v[22:23], v[220:221]
	v_pk_mul_f32 v[16:17], v[16:17], v[222:223]
	v_pk_mul_f32 v[18:19], v[18:19], v[224:225]
	global_store_dwordx4 v129, v[28:31], s[76:77] sc0 sc1
	global_store_dwordx4 v129, v[24:27], s[76:77] offset:16 sc0 sc1
	global_store_dwordx4 v129, v[20:23], s[76:77] offset:128 sc0 sc1
	global_store_dwordx4 v129, v[16:19], s[76:77] offset:144 sc0 sc1
	s_add_u32 s76, s76, 0x10000
	s_addc_u32 s77, s77, 0
	v_pk_mul_f32 v[12:13], v[12:13], v[208:209] op_sel_hi:[1,0]
	v_pk_mul_f32 v[14:15], v[14:15], v[208:209] op_sel_hi:[1,0]
	v_pk_mul_f32 v[8:9], v[8:9], v[208:209] op_sel_hi:[1,0]
	v_pk_mul_f32 v[10:11], v[10:11], v[208:209] op_sel_hi:[1,0]
	v_pk_mul_f32 v[4:5], v[4:5], v[208:209] op_sel_hi:[1,0]
	v_pk_mul_f32 v[6:7], v[6:7], v[208:209] op_sel_hi:[1,0]
	v_pk_mul_f32 v[0:1], v[0:1], v[208:209] op_sel_hi:[1,0]
	v_pk_mul_f32 v[2:3], v[2:3], v[208:209] op_sel_hi:[1,0]
	v_pk_mul_f32 v[12:13], v[12:13], v[210:211]
	v_pk_mul_f32 v[14:15], v[14:15], v[212:213]
	v_pk_mul_f32 v[8:9], v[8:9], v[214:215]
	v_pk_mul_f32 v[10:11], v[10:11], v[216:217]
	v_pk_mul_f32 v[4:5], v[4:5], v[218:219]
	v_pk_mul_f32 v[6:7], v[6:7], v[220:221]
	v_pk_mul_f32 v[0:1], v[0:1], v[222:223]
	v_pk_mul_f32 v[2:3], v[2:3], v[224:225]
	global_store_dwordx4 v129, v[12:15], s[76:77] sc0 sc1
	global_store_dwordx4 v129, v[8:11], s[76:77] offset:16 sc0 sc1
	global_store_dwordx4 v129, v[4:7], s[76:77] offset:128 sc0 sc1
	global_store_dwordx4 v129, v[0:3], s[76:77] offset:144 sc0 sc1
	s_cmpk_gt_u32 s17, 0xff
	s_cbranch_scc0 .Lf11_w0_b
	s_barrier
